# v29 + one static s_setprio 1 for waves 4-7 during the mixer-attention phase (reset to 0 at its end)
# speedup vs baseline: 1.0010x; 1.0010x over previous
_Z9trunk_fwd4Args:
	v_readfirstlane_b32 s100, v0
	s_nop 0
	s_lshr_b32 s100, s100, 8
	s_load_dword s3, s[0:1], 0xf0
	s_add_u32 s4, s0, 0xf0
	s_addc_u32 s5, s1, 0
	v_readfirstlane_b32 s12, v0
	v_writelane_b32 v246, s4, 0
	s_mov_b32 s13, s2
	s_nop 0
	v_writelane_b32 v246, s5, 1
	s_waitcnt lgkmcnt(0)
	v_writelane_b32 v246, s3, 2
	s_and_b32 s3, s3, 7
	s_cmp_eq_u32 s3, 0
	s_cselect_b64 s[34:35], -1, 0
	s_cmp_lg_u32 s3, 0
	s_cselect_b64 s[4:5], -1, 0
	s_and_b64 vcc, exec, s[4:5]
	s_cbranch_vccnz .LBB0_2
	s_load_dword s3, s[0:1], 0xf0
	s_ashr_i32 s6, s2, 31
	s_lshr_b32 s6, s6, 29
	s_add_i32 s6, s2, s6
	s_ashr_i32 s7, s6, 3
	s_and_b32 s6, s6, -8
	s_waitcnt lgkmcnt(0)
	s_ashr_i32 s3, s3, 3
	s_sub_i32 s6, s2, s6
	s_mul_i32 s3, s3, s6
	s_add_i32 s13, s3, s7

.LBB0_474:
	s_andn2_b64 vcc, exec, s[0:1]
	s_mov_b32 s30, s56
	s_cbranch_vccnz .LBB0_1025
	s_mul_i32 s0, s56, 24
	v_readlane_b32 s1, v245, 13
	v_readlane_b32 s2, v243, 59
	s_or_b32 s0, s0, s1
	v_readlane_b32 s3, v243, 60
	s_mov_b32 s1, s3
	s_lshl_b32 s0, s0, 6
	v_writelane_b32 v243, s2, 59
	s_lshl_b64 s[0:1], s[0:1], 2
	v_mov_b32_e32 v1, v0
	v_writelane_b32 v243, s3, 60
	v_readlane_b32 s2, v244, 32
	s_add_u32 s2, s2, s0
	v_readlane_b32 s0, v244, 33
	s_addc_u32 s3, s0, s1
	s_cmp_eq_u32 s100, 0
	s_cbranch_scc1 .Lattn_noprio
	s_setprio 1
.Lattn_noprio:
	v_writelane_b32 v242, s2, 6
	v_cmp_eq_u32_e64 s[36:37], 0, v1
	s_nop 0
	v_writelane_b32 v242, s3, 7
	s_and_saveexec_b64 s[0:1], s[36:37]
	s_cbranch_execz .LBB0_480
	s_mov_b64 s[4:5], exec
	v_mbcnt_lo_u32_b32 v1, s4, 0
	v_mbcnt_hi_u32_b32 v1, s5, v1
	v_cmp_eq_u32_e32 vcc, 0, v1
	s_and_saveexec_b64 s[2:3], vcc
	s_cbranch_execz .LBB0_478
	s_bcnt1_i32_b64 s4, s[4:5]
	v_mov_b32_e32 v2, s4
	v_readlane_b32 s4, v242, 6
	v_readlane_b32 s5, v242, 7
	s_nop 4
	global_atomic_add v2, v163, v2, s[4:5] sc0

.LBB0_808:
	s_setprio 0
	s_or_b32 s8, s31, 3
	v_readlane_b32 s2, v246, 3
	v_readlane_b32 s3, v246, 4
	s_cmp_gt_i32 s2, s8
	s_cselect_b64 s[0:1], -1, 0
	s_cmp_ge_i32 s8, s3
	s_cselect_b64 s[2:3], -1, 0
	s_or_b64 s[0:1], s[0:1], s[2:3]
	s_and_b64 vcc, exec, s[0:1]
	s_cbranch_vccnz .LBB0_1025
	s_waitcnt vmcnt(0)
	s_barrier
	s_mov_b64 s[0:1], exec
	v_readlane_b32 s2, v243, 61
	v_readlane_b32 s3, v243, 62
	s_and_b64 s[2:3], s[0:1], s[2:3]
	s_mov_b64 exec, s[2:3]
	s_cbranch_execz .LBB0_1024
	v_readlane_b32 s2, v246, 16
	s_waitcnt vmcnt(0) expcnt(0) lgkmcnt(0)
	s_nop 0
	v_mov_b32_e32 v1, s2
	ds_read_b32 v3, v1
	ds_read_b32 v2, v1 offset:4
	s_waitcnt lgkmcnt(1)
	v_cmp_ne_u32_e32 vcc, 0, v3
	s_cbranch_vccnz .LBB0_991
	v_readlane_b32 s2, v245, 44
	v_readlane_b32 s3, v245, 45
	s_andn2_b64 vcc, exec, s[2:3]
	v_readlane_b32 s9, v246, 15
	s_cbranch_vccnz .LBB0_813
	v_readlane_b32 s4, v246, 0
	v_readlane_b32 s5, v246, 1
	s_load_dwordx2 s[2:3], s[4:5], 0x4
	v_readlane_b32 s4, v246, 2
	s_waitcnt lgkmcnt(0)
	s_mul_i32 s2, s2, s4
	s_mul_i32 s9, s2, s3
